# v38
# speedup vs baseline: 1.0055x; 1.0020x over previous
; __device__ __forceinline__ unsigned cvt_pk_bf16(float lo, float hi) { const f32x2c v = {lo, hi}; const bf16x2c b = __builtin_convertvector(v, bf16x2c); return __builtin_bit_cast(unsigned, b); }
; __device__ __forceinline__ float bf_lo(unsigned w) { return __uint_as_float(w << 16); }
; __device__ __forceinline__ float bf_hi(unsigned w) { return __uint_as_float(w & 0xffff0000u); }
; __device__ __forceinline__ void hgrn_passC(LAS unsigned char* lds, const float* LOGF, bf16_t* HQ, const bf16_t* HI, const bf16_t* HGS, const bf16_t* LS, const float* nw, int unit) {
;     ...
;     const float rstd = __builtin_amdgcn_rsqf((red[16 * tt + r] + red[64 + 16 * tt + r]) * (1.0f / 128.0f) + pg8::EPS);
; #pragma unroll
;     for (int j = 0; j < 4; ++j) { const int v0 = 16 * (4 * vh4 + j) + 4 * q; const size_t off = (row0 + 16 * tt + r) * 1024 + h * 128 + v0;
;         const f32x4 w4 = *(const f32x4*)(nw + v0); const u32x2 gw = *(const u32x2*)(HGS + off);
;         const f32x4 y = o[j] * rstd * w4 * (f32x4){bf_lo(gw.x), bf_hi(gw.x), bf_lo(gw.y), bf_hi(gw.y)};
;         u32x2 p; p.x = cvt_pk_bf16(y[0], y[1]); p.y = cvt_pk_bf16(y[2], y[3]); *(u32x2*)(HQ + off) = p; }
;     __syncthreads();
.LBB0_651:
	s_or_b64 exec, exec, s[40:41]
	s_waitcnt lgkmcnt(0)
	v_or_b32_e32 v6, s38, v73
	v_mov_b32_e32 v7, s39
	v_or_b32_e32 v10, v74, v71
	v_lshlrev_b64 v[12:13], 10, v[6:7]
	v_or_b32_e32 v12, s47, v12
	v_ashrrev_i32_e32 v11, 31, v10
	s_add_u32 s36, s36, 0x10000000
	v_lshl_add_u64 v[14:15], v[12:13], 0, v[10:11]
	s_addc_u32 s37, s37, 0
	v_lshlrev_b64 v[14:15], 1, v[14:15]
	v_lshl_add_u64 v[20:21], v[10:11], 2, s[34:35]
	v_lshl_add_u64 v[22:23], s[36:37], 0, v[14:15]
	s_barrier
	global_load_dwordx4 v[6:9], v[20:21], off
	v_lshlrev_b32_e32 v5, 2, v70
	global_load_dwordx2 v[22:23], v[22:23], off
	v_add3_u32 v4, 0, v5, v4
	ds_read2st64_b32 v[4:5], v4 offset0:8 offset1:9
	v_or_b32_e32 v24, 16, v10
	v_ashrrev_i32_e32 v25, 31, v24
	s_add_i32 s46, s46, s16
	s_add_i32 s6, s6, s7
	s_waitcnt lgkmcnt(0)
	v_add_f32_e32 v4, v4, v5
	v_fmamk_f32 v4, v4, 0x3c000000, v65
	v_rsq_f32_e32 v26, v4
	v_lshl_add_u64 v[4:5], v[12:13], 0, v[24:25]
	v_lshlrev_b64 v[24:25], 1, v[4:5]
	v_lshl_add_u64 v[166:167], s[36:37], 0, v[24:25]
	v_or_b32_e32 v146, 32, v10
	v_or_b32_e32 v156, 48, v10
	v_ashrrev_i32_e32 v147, 31, v146
	v_ashrrev_i32_e32 v157, 31, v156
	global_load_dwordx4 v[140:143], v[20:21], off offset:64
	global_load_dwordx2 v[144:145], v[166:167], off
	v_lshl_add_u64 v[146:147], v[12:13], 0, v[146:147]
	v_lshl_add_u64 v[156:157], v[12:13], 0, v[156:157]
	v_lshlrev_b64 v[146:147], 1, v[146:147]
	v_lshlrev_b64 v[156:157], 1, v[156:157]
	v_lshl_add_u64 v[148:149], s[36:37], 0, v[146:147]
	v_lshl_add_u64 v[158:159], s[36:37], 0, v[156:157]
	global_load_dwordx4 v[150:153], v[20:21], off offset:128
	global_load_dwordx2 v[154:155], v[148:149], off
	global_load_dwordx4 v[160:163], v[20:21], off offset:192
	global_load_dwordx2 v[164:165], v[158:159], off
	v_lshl_add_u64 v[4:5], s[30:31], 0, v[14:15]
	v_pk_mul_f32 v[14:15], v[36:37], v[26:27] op_sel_hi:[1,0]
	v_pk_mul_f32 v[28:29], v[38:39], v[26:27] op_sel_hi:[1,0]
	v_pk_mul_f32 v[0:1], v[0:1], v[26:27] op_sel_hi:[1,0]
	v_pk_mul_f32 v[2:3], v[2:3], v[26:27] op_sel_hi:[1,0]
	s_add_u32 s10, s10, s12
	s_addc_u32 s11, s11, s13
	s_cmpk_gt_i32 s46, 0x7ff
	s_waitcnt vmcnt(7)
	v_pk_mul_f32 v[8:9], v[8:9], v[28:29]
	v_pk_mul_f32 v[6:7], v[6:7], v[14:15]
	s_waitcnt vmcnt(6)
	v_lshlrev_b32_e32 v14, 16, v22
	v_and_b32_e32 v15, 0xffff0000, v22
	v_lshlrev_b32_e32 v22, 16, v23
	v_and_b32_e32 v23, 0xffff0000, v23
	v_pk_mul_f32 v[8:9], v[8:9], v[22:23]
	v_pk_mul_f32 v[6:7], v[6:7], v[14:15]
	v_or_b32_e32 v14, 32, v10
	v_cvt_pk_bf16_f32 v6, v6, v7
	v_cvt_pk_bf16_f32 v7, v8, v9
	global_store_dwordx2 v[4:5], v[6:7], off
	v_lshl_add_u64 v[22:23], s[30:31], 0, v[24:25]
	v_pk_mul_f32 v[24:25], v[32:33], v[26:27] op_sel_hi:[1,0]
	v_pk_mul_f32 v[28:29], v[34:35], v[26:27] op_sel_hi:[1,0]
	v_ashrrev_i32_e32 v15, 31, v14
	v_lshl_add_u64 v[14:15], v[12:13], 0, v[14:15]
	v_lshlrev_b64 v[14:15], 1, v[14:15]
	v_or_b32_e32 v10, 48, v10
	v_ashrrev_i32_e32 v11, 31, v10
	v_lshl_add_u64 v[10:11], v[12:13], 0, v[10:11]
	v_lshl_add_u64 v[12:13], s[30:31], 0, v[14:15]
	v_lshlrev_b64 v[10:11], 1, v[10:11]
	s_waitcnt vmcnt(6)
	v_pk_mul_f32 v[6:7], v[142:143], v[28:29]
	v_pk_mul_f32 v[4:5], v[140:141], v[24:25]
	s_waitcnt vmcnt(5)
	v_lshlrev_b32_e32 v24, 16, v144
	v_and_b32_e32 v25, 0xffff0000, v144
	v_lshlrev_b32_e32 v8, 16, v145
	v_and_b32_e32 v9, 0xffff0000, v145
	v_pk_mul_f32 v[6:7], v[6:7], v[8:9]
	v_pk_mul_f32 v[4:5], v[4:5], v[24:25]
	v_cvt_pk_bf16_f32 v4, v4, v5
	v_cvt_pk_bf16_f32 v5, v6, v7
	global_store_dwordx2 v[22:23], v[4:5], off
	v_pk_mul_f32 v[14:15], v[16:17], v[26:27] op_sel_hi:[1,0]
	v_pk_mul_f32 v[16:17], v[18:19], v[26:27] op_sel_hi:[1,0]
	s_waitcnt vmcnt(5)
	v_pk_mul_f32 v[4:5], v[150:151], v[14:15]
	v_pk_mul_f32 v[6:7], v[152:153], v[16:17]
	s_waitcnt vmcnt(4)
	v_lshlrev_b32_e32 v14, 16, v154
	v_and_b32_e32 v15, 0xffff0000, v154
	v_lshlrev_b32_e32 v8, 16, v155
	v_and_b32_e32 v9, 0xffff0000, v155
	v_pk_mul_f32 v[6:7], v[6:7], v[8:9]
	v_pk_mul_f32 v[4:5], v[4:5], v[14:15]
	v_cvt_pk_bf16_f32 v4, v4, v5
	v_cvt_pk_bf16_f32 v5, v6, v7
	global_store_dwordx2 v[12:13], v[4:5], off
	v_lshl_add_u64 v[10:11], s[30:31], 0, v[10:11]
	s_waitcnt vmcnt(4)
	v_pk_mul_f32 v[2:3], v[2:3], v[162:163]
	v_pk_mul_f32 v[0:1], v[0:1], v[160:161]
	s_waitcnt vmcnt(3)
	v_lshlrev_b32_e32 v4, 16, v164
	v_and_b32_e32 v5, 0xffff0000, v164
	v_lshlrev_b32_e32 v6, 16, v165
	v_and_b32_e32 v7, 0xffff0000, v165
	v_pk_mul_f32 v[2:3], v[2:3], v[6:7]
	v_pk_mul_f32 v[0:1], v[0:1], v[4:5]
	s_nop 0
	v_cvt_pk_bf16_f32 v0, v0, v1
	v_cvt_pk_bf16_f32 v1, v2, v3
	global_store_dwordx2 v[10:11], v[0:1], off
	s_barrier
	s_cbranch_scc1 .LBB0_658
